# pooled loop: prefetching fast path (all 32 row loads issued up front) for tasks with t0!=0
# baseline (speedup 1.0000x reference)
.LBB0_198:
	s_nop 0
	v_readfirstlane_b32 s42, v20
	s_bfe_u32 s43, s42, 0x70008
	s_cmp_lg_u32 s43, 0
	s_cbranch_scc1 .Lpool_fast
	v_ashrrev_i32_e32 v1, 3, v20
	v_and_b32_e32 v16, 0xffffffe0, v1
	v_ashrrev_i32_e32 v17, 31, v16
	v_bfe_u32 v6, v20, 6, 2
	v_and_b32_e32 v22, 0xfe0, v1
	v_lshlrev_b64 v[18:19], 12, v[16:17]
	v_mov_b32_e32 v1, v0
	v_lshlrev_b32_e64 v23, v6, 2
	v_lshl_add_u64 v[14:15], v[2:3], 0, v[18:19]
	s_mov_b64 s[42:43], 0
	s_mov_b32 s46, 1
	v_mov_b64_e32 v[6:7], v[0:1]
	v_mov_b64_e32 v[8:9], v[0:1]
	v_mov_b64_e32 v[10:11], v[0:1]
	v_mov_b64_e32 v[12:13], v[0:1]
	s_branch .LBB0_200

.Lpool_fast:
	s_bfe_u32 s16, s42, 0x20006
	s_lshr_b32 s17, s42, 8
	s_lshl_b32 s17, s17, 17
	s_add_u32 s44, s28, 0x2d200000
	s_addc_u32 s45, s29, 0
	s_add_u32 s44, s44, s17
	s_addc_u32 s45, s45, 0
	s_add_u32 s98, s28, 0x31200000
	s_addc_u32 s99, s29, 0
	s_add_u32 s98, s98, s17
	s_addc_u32 s99, s99, 0
	s_lshl_b32 s101, 2, s16
	s_sub_u32 s101, s101, 1
	s_sub_u32 s100, 0x7e, s16
	s_lshl_b32 s100, s100, 23
	v_and_b32_e32 v16, 0xff, v20
	v_lshlrev_b32_e32 v16, 4, v16
	s_sub_u32 s46, s44, 0x1000
	s_subb_u32 s47, s45, 0
	global_load_dwordx4 v[36:39], v16, s[46:47]
	s_cmp_eq_u32 s101, 1
	s_cbranch_scc1 .Lpool_wdone
	s_sub_u32 s46, s46, 0x1000
	s_subb_u32 s47, s47, 0
	global_load_dwordx4 v[40:43], v16, s[46:47]
	s_sub_u32 s46, s46, 0x1000
	s_subb_u32 s47, s47, 0
	global_load_dwordx4 v[44:47], v16, s[46:47]
	s_cmp_eq_u32 s101, 3
	s_cbranch_scc1 .Lpool_wdone
	s_sub_u32 s46, s46, 0x1000
	s_subb_u32 s47, s47, 0
	global_load_dwordx4 v[48:51], v16, s[46:47]
	s_sub_u32 s46, s46, 0x1000
	s_subb_u32 s47, s47, 0
	global_load_dwordx4 v[52:55], v16, s[46:47]
	s_sub_u32 s46, s46, 0x1000
	s_subb_u32 s47, s47, 0
	global_load_dwordx4 v[56:59], v16, s[46:47]
	s_sub_u32 s46, s46, 0x1000
	s_subb_u32 s47, s47, 0
	global_load_dwordx4 v[60:63], v16, s[46:47]
	s_cmp_eq_u32 s101, 7
	s_cbranch_scc1 .Lpool_wdone
	s_sub_u32 s46, s46, 0x1000
	s_subb_u32 s47, s47, 0
	global_load_dwordx4 v[64:67], v16, s[46:47]
	s_sub_u32 s46, s46, 0x1000
	s_subb_u32 s47, s47, 0
	global_load_dwordx4 v[68:71], v16, s[46:47]
	s_sub_u32 s46, s46, 0x1000
	s_subb_u32 s47, s47, 0
	global_load_dwordx4 v[72:75], v16, s[46:47]
	s_sub_u32 s46, s46, 0x1000
	s_subb_u32 s47, s47, 0
	global_load_dwordx4 v[76:79], v16, s[46:47]
	s_sub_u32 s46, s46, 0x1000
	s_subb_u32 s47, s47, 0
	global_load_dwordx4 v[80:83], v16, s[46:47]
	s_sub_u32 s46, s46, 0x1000
	s_subb_u32 s47, s47, 0
	global_load_dwordx4 v[84:87], v16, s[46:47]
	s_sub_u32 s46, s46, 0x1000
	s_subb_u32 s47, s47, 0
	global_load_dwordx4 v[88:91], v16, s[46:47]
	s_sub_u32 s46, s46, 0x1000
	s_subb_u32 s47, s47, 0
	global_load_dwordx4 v[92:95], v16, s[46:47]
.Lpool_wdone:
	v_mov_b32_e32 v232, 0
	v_mov_b32_e32 v233, 0
	v_mov_b32_e32 v234, 0
	v_mov_b32_e32 v235, 0
	v_mov_b32_e32 v236, 0
	v_mov_b32_e32 v237, 0
	v_mov_b32_e32 v238, 0
	v_mov_b32_e32 v239, 0
	s_mov_b32 s17, 0
.Lpool_chunk:
	global_load_dwordx4 v[96:99], v16, s[44:45]
	global_load_dwordx4 v[160:163], v16, s[46:47]
	s_add_u32 s44, s44, 0x1000
	s_addc_u32 s45, s45, 0
	s_add_u32 s46, s46, 0x1000
	s_addc_u32 s47, s47, 0
	global_load_dwordx4 v[100:103], v16, s[44:45]
	global_load_dwordx4 v[164:167], v16, s[46:47]
	s_add_u32 s44, s44, 0x1000
	s_addc_u32 s45, s45, 0
	s_add_u32 s46, s46, 0x1000
	s_addc_u32 s47, s47, 0
	global_load_dwordx4 v[104:107], v16, s[44:45]
	global_load_dwordx4 v[168:171], v16, s[46:47]
	s_add_u32 s44, s44, 0x1000
	s_addc_u32 s45, s45, 0
	s_add_u32 s46, s46, 0x1000
	s_addc_u32 s47, s47, 0
	global_load_dwordx4 v[108:111], v16, s[44:45]
	global_load_dwordx4 v[172:175], v16, s[46:47]
	s_add_u32 s44, s44, 0x1000
	s_addc_u32 s45, s45, 0
	s_add_u32 s46, s46, 0x1000
	s_addc_u32 s47, s47, 0
	global_load_dwordx4 v[112:115], v16, s[44:45]
	global_load_dwordx4 v[176:179], v16, s[46:47]
	s_add_u32 s44, s44, 0x1000
	s_addc_u32 s45, s45, 0
	s_add_u32 s46, s46, 0x1000
	s_addc_u32 s47, s47, 0
	global_load_dwordx4 v[116:119], v16, s[44:45]
	global_load_dwordx4 v[180:183], v16, s[46:47]
	s_add_u32 s44, s44, 0x1000
	s_addc_u32 s45, s45, 0
	s_add_u32 s46, s46, 0x1000
	s_addc_u32 s47, s47, 0
	global_load_dwordx4 v[120:123], v16, s[44:45]
	global_load_dwordx4 v[184:187], v16, s[46:47]
	s_add_u32 s44, s44, 0x1000
	s_addc_u32 s45, s45, 0
	s_add_u32 s46, s46, 0x1000
	s_addc_u32 s47, s47, 0
	global_load_dwordx4 v[124:127], v16, s[44:45]
	global_load_dwordx4 v[188:191], v16, s[46:47]
	s_add_u32 s44, s44, 0x1000
	s_addc_u32 s45, s45, 0
	s_add_u32 s46, s46, 0x1000
	s_addc_u32 s47, s47, 0
	global_load_dwordx4 v[128:131], v16, s[44:45]
	global_load_dwordx4 v[192:195], v16, s[46:47]
	s_add_u32 s44, s44, 0x1000
	s_addc_u32 s45, s45, 0
	s_add_u32 s46, s46, 0x1000
	s_addc_u32 s47, s47, 0
	global_load_dwordx4 v[132:135], v16, s[44:45]
	global_load_dwordx4 v[196:199], v16, s[46:47]
	s_add_u32 s44, s44, 0x1000
	s_addc_u32 s45, s45, 0
	s_add_u32 s46, s46, 0x1000
	s_addc_u32 s47, s47, 0
	global_load_dwordx4 v[136:139], v16, s[44:45]
	global_load_dwordx4 v[200:203], v16, s[46:47]
	s_add_u32 s44, s44, 0x1000
	s_addc_u32 s45, s45, 0
	s_add_u32 s46, s46, 0x1000
	s_addc_u32 s47, s47, 0
	global_load_dwordx4 v[140:143], v16, s[44:45]
	global_load_dwordx4 v[208:211], v16, s[46:47]
	s_add_u32 s44, s44, 0x1000
	s_addc_u32 s45, s45, 0
	s_add_u32 s46, s46, 0x1000
	s_addc_u32 s47, s47, 0
	global_load_dwordx4 v[144:147], v16, s[44:45]
	global_load_dwordx4 v[212:215], v16, s[46:47]
	s_add_u32 s44, s44, 0x1000
	s_addc_u32 s45, s45, 0
	s_add_u32 s46, s46, 0x1000
	s_addc_u32 s47, s47, 0
	global_load_dwordx4 v[148:151], v16, s[44:45]
	global_load_dwordx4 v[216:219], v16, s[46:47]
	s_add_u32 s44, s44, 0x1000
	s_addc_u32 s45, s45, 0
	s_add_u32 s46, s46, 0x1000
	s_addc_u32 s47, s47, 0
	global_load_dwordx4 v[152:155], v16, s[44:45]
	global_load_dwordx4 v[220:223], v16, s[46:47]
	s_add_u32 s44, s44, 0x1000
	s_addc_u32 s45, s45, 0
	s_add_u32 s46, s46, 0x1000
	s_addc_u32 s47, s47, 0
	global_load_dwordx4 v[156:159], v16, s[44:45]
	global_load_dwordx4 v[228:231], v16, s[46:47]
	s_add_u32 s44, s44, 0x1000
	s_addc_u32 s45, s45, 0
	s_add_u32 s46, s46, 0x1000
	s_addc_u32 s47, s47, 0
	s_cmp_lg_u32 s17, 0
	s_cbranch_scc1 .Lpool_rows
	s_waitcnt vmcnt(32)
	v_lshlrev_b32_e32 v240, 16, v36
	v_and_b32_e32 v241, 0xffff0000, v36
	v_lshlrev_b32_e32 v242, 16, v37
	v_and_b32_e32 v243, 0xffff0000, v37
	v_lshlrev_b32_e32 v244, 16, v38
	v_and_b32_e32 v245, 0xffff0000, v38
	v_lshlrev_b32_e32 v246, 16, v39
	v_and_b32_e32 v247, 0xffff0000, v39
	v_pk_add_f32 v[232:233], v[232:233], v[240:241]
	v_pk_add_f32 v[234:235], v[234:235], v[242:243]
	v_pk_add_f32 v[236:237], v[236:237], v[244:245]
	v_pk_add_f32 v[238:239], v[238:239], v[246:247]
	s_cmp_eq_u32 s101, 1
	s_cbranch_scc1 .Lpool_rows
	v_lshlrev_b32_e32 v240, 16, v40
	v_and_b32_e32 v241, 0xffff0000, v40
	v_lshlrev_b32_e32 v242, 16, v41
	v_and_b32_e32 v243, 0xffff0000, v41
	v_lshlrev_b32_e32 v244, 16, v42
	v_and_b32_e32 v245, 0xffff0000, v42
	v_lshlrev_b32_e32 v246, 16, v43
	v_and_b32_e32 v247, 0xffff0000, v43
	v_pk_add_f32 v[232:233], v[232:233], v[240:241]
	v_pk_add_f32 v[234:235], v[234:235], v[242:243]
	v_pk_add_f32 v[236:237], v[236:237], v[244:245]
	v_pk_add_f32 v[238:239], v[238:239], v[246:247]
	v_lshlrev_b32_e32 v240, 16, v44
	v_and_b32_e32 v241, 0xffff0000, v44
	v_lshlrev_b32_e32 v242, 16, v45
	v_and_b32_e32 v243, 0xffff0000, v45
	v_lshlrev_b32_e32 v244, 16, v46
	v_and_b32_e32 v245, 0xffff0000, v46
	v_lshlrev_b32_e32 v246, 16, v47
	v_and_b32_e32 v247, 0xffff0000, v47
	v_pk_add_f32 v[232:233], v[232:233], v[240:241]
	v_pk_add_f32 v[234:235], v[234:235], v[242:243]
	v_pk_add_f32 v[236:237], v[236:237], v[244:245]
	v_pk_add_f32 v[238:239], v[238:239], v[246:247]
	s_cmp_eq_u32 s101, 3
	s_cbranch_scc1 .Lpool_rows
	v_lshlrev_b32_e32 v240, 16, v48
	v_and_b32_e32 v241, 0xffff0000, v48
	v_lshlrev_b32_e32 v242, 16, v49
	v_and_b32_e32 v243, 0xffff0000, v49
	v_lshlrev_b32_e32 v244, 16, v50
	v_and_b32_e32 v245, 0xffff0000, v50
	v_lshlrev_b32_e32 v246, 16, v51
	v_and_b32_e32 v247, 0xffff0000, v51
	v_pk_add_f32 v[232:233], v[232:233], v[240:241]
	v_pk_add_f32 v[234:235], v[234:235], v[242:243]
	v_pk_add_f32 v[236:237], v[236:237], v[244:245]
	v_pk_add_f32 v[238:239], v[238:239], v[246:247]
	v_lshlrev_b32_e32 v240, 16, v52
	v_and_b32_e32 v241, 0xffff0000, v52
	v_lshlrev_b32_e32 v242, 16, v53
	v_and_b32_e32 v243, 0xffff0000, v53
	v_lshlrev_b32_e32 v244, 16, v54
	v_and_b32_e32 v245, 0xffff0000, v54
	v_lshlrev_b32_e32 v246, 16, v55
	v_and_b32_e32 v247, 0xffff0000, v55
	v_pk_add_f32 v[232:233], v[232:233], v[240:241]
	v_pk_add_f32 v[234:235], v[234:235], v[242:243]
	v_pk_add_f32 v[236:237], v[236:237], v[244:245]
	v_pk_add_f32 v[238:239], v[238:239], v[246:247]
	v_lshlrev_b32_e32 v240, 16, v56
	v_and_b32_e32 v241, 0xffff0000, v56
	v_lshlrev_b32_e32 v242, 16, v57
	v_and_b32_e32 v243, 0xffff0000, v57
	v_lshlrev_b32_e32 v244, 16, v58
	v_and_b32_e32 v245, 0xffff0000, v58
	v_lshlrev_b32_e32 v246, 16, v59
	v_and_b32_e32 v247, 0xffff0000, v59
	v_pk_add_f32 v[232:233], v[232:233], v[240:241]
	v_pk_add_f32 v[234:235], v[234:235], v[242:243]
	v_pk_add_f32 v[236:237], v[236:237], v[244:245]
	v_pk_add_f32 v[238:239], v[238:239], v[246:247]
	v_lshlrev_b32_e32 v240, 16, v60
	v_and_b32_e32 v241, 0xffff0000, v60
	v_lshlrev_b32_e32 v242, 16, v61
	v_and_b32_e32 v243, 0xffff0000, v61
	v_lshlrev_b32_e32 v244, 16, v62
	v_and_b32_e32 v245, 0xffff0000, v62
	v_lshlrev_b32_e32 v246, 16, v63
	v_and_b32_e32 v247, 0xffff0000, v63
	v_pk_add_f32 v[232:233], v[232:233], v[240:241]
	v_pk_add_f32 v[234:235], v[234:235], v[242:243]
	v_pk_add_f32 v[236:237], v[236:237], v[244:245]
	v_pk_add_f32 v[238:239], v[238:239], v[246:247]
	s_cmp_eq_u32 s101, 7
	s_cbranch_scc1 .Lpool_rows
	v_lshlrev_b32_e32 v240, 16, v64
	v_and_b32_e32 v241, 0xffff0000, v64
	v_lshlrev_b32_e32 v242, 16, v65
	v_and_b32_e32 v243, 0xffff0000, v65
	v_lshlrev_b32_e32 v244, 16, v66
	v_and_b32_e32 v245, 0xffff0000, v66
	v_lshlrev_b32_e32 v246, 16, v67
	v_and_b32_e32 v247, 0xffff0000, v67
	v_pk_add_f32 v[232:233], v[232:233], v[240:241]
	v_pk_add_f32 v[234:235], v[234:235], v[242:243]
	v_pk_add_f32 v[236:237], v[236:237], v[244:245]
	v_pk_add_f32 v[238:239], v[238:239], v[246:247]
	v_lshlrev_b32_e32 v240, 16, v68
	v_and_b32_e32 v241, 0xffff0000, v68
	v_lshlrev_b32_e32 v242, 16, v69
	v_and_b32_e32 v243, 0xffff0000, v69
	v_lshlrev_b32_e32 v244, 16, v70
	v_and_b32_e32 v245, 0xffff0000, v70
	v_lshlrev_b32_e32 v246, 16, v71
	v_and_b32_e32 v247, 0xffff0000, v71
	v_pk_add_f32 v[232:233], v[232:233], v[240:241]
	v_pk_add_f32 v[234:235], v[234:235], v[242:243]
	v_pk_add_f32 v[236:237], v[236:237], v[244:245]
	v_pk_add_f32 v[238:239], v[238:239], v[246:247]
	v_lshlrev_b32_e32 v240, 16, v72
	v_and_b32_e32 v241, 0xffff0000, v72
	v_lshlrev_b32_e32 v242, 16, v73
	v_and_b32_e32 v243, 0xffff0000, v73
	v_lshlrev_b32_e32 v244, 16, v74
	v_and_b32_e32 v245, 0xffff0000, v74
	v_lshlrev_b32_e32 v246, 16, v75
	v_and_b32_e32 v247, 0xffff0000, v75
	v_pk_add_f32 v[232:233], v[232:233], v[240:241]
	v_pk_add_f32 v[234:235], v[234:235], v[242:243]
	v_pk_add_f32 v[236:237], v[236:237], v[244:245]
	v_pk_add_f32 v[238:239], v[238:239], v[246:247]
	v_lshlrev_b32_e32 v240, 16, v76
	v_and_b32_e32 v241, 0xffff0000, v76
	v_lshlrev_b32_e32 v242, 16, v77
	v_and_b32_e32 v243, 0xffff0000, v77
	v_lshlrev_b32_e32 v244, 16, v78
	v_and_b32_e32 v245, 0xffff0000, v78
	v_lshlrev_b32_e32 v246, 16, v79
	v_and_b32_e32 v247, 0xffff0000, v79
	v_pk_add_f32 v[232:233], v[232:233], v[240:241]
	v_pk_add_f32 v[234:235], v[234:235], v[242:243]
	v_pk_add_f32 v[236:237], v[236:237], v[244:245]
	v_pk_add_f32 v[238:239], v[238:239], v[246:247]
	v_lshlrev_b32_e32 v240, 16, v80
	v_and_b32_e32 v241, 0xffff0000, v80
	v_lshlrev_b32_e32 v242, 16, v81
	v_and_b32_e32 v243, 0xffff0000, v81
	v_lshlrev_b32_e32 v244, 16, v82
	v_and_b32_e32 v245, 0xffff0000, v82
	v_lshlrev_b32_e32 v246, 16, v83
	v_and_b32_e32 v247, 0xffff0000, v83
	v_pk_add_f32 v[232:233], v[232:233], v[240:241]
	v_pk_add_f32 v[234:235], v[234:235], v[242:243]
	v_pk_add_f32 v[236:237], v[236:237], v[244:245]
	v_pk_add_f32 v[238:239], v[238:239], v[246:247]
	v_lshlrev_b32_e32 v240, 16, v84
	v_and_b32_e32 v241, 0xffff0000, v84
	v_lshlrev_b32_e32 v242, 16, v85
	v_and_b32_e32 v243, 0xffff0000, v85
	v_lshlrev_b32_e32 v244, 16, v86
	v_and_b32_e32 v245, 0xffff0000, v86
	v_lshlrev_b32_e32 v246, 16, v87
	v_and_b32_e32 v247, 0xffff0000, v87
	v_pk_add_f32 v[232:233], v[232:233], v[240:241]
	v_pk_add_f32 v[234:235], v[234:235], v[242:243]
	v_pk_add_f32 v[236:237], v[236:237], v[244:245]
	v_pk_add_f32 v[238:239], v[238:239], v[246:247]
	v_lshlrev_b32_e32 v240, 16, v88
	v_and_b32_e32 v241, 0xffff0000, v88
	v_lshlrev_b32_e32 v242, 16, v89
	v_and_b32_e32 v243, 0xffff0000, v89
	v_lshlrev_b32_e32 v244, 16, v90
	v_and_b32_e32 v245, 0xffff0000, v90
	v_lshlrev_b32_e32 v246, 16, v91
	v_and_b32_e32 v247, 0xffff0000, v91
	v_pk_add_f32 v[232:233], v[232:233], v[240:241]
	v_pk_add_f32 v[234:235], v[234:235], v[242:243]
	v_pk_add_f32 v[236:237], v[236:237], v[244:245]
	v_pk_add_f32 v[238:239], v[238:239], v[246:247]
	v_lshlrev_b32_e32 v240, 16, v92
	v_and_b32_e32 v241, 0xffff0000, v92
	v_lshlrev_b32_e32 v242, 16, v93
	v_and_b32_e32 v243, 0xffff0000, v93
	v_lshlrev_b32_e32 v244, 16, v94
	v_and_b32_e32 v245, 0xffff0000, v94
	v_lshlrev_b32_e32 v246, 16, v95
	v_and_b32_e32 v247, 0xffff0000, v95
	v_pk_add_f32 v[232:233], v[232:233], v[240:241]
	v_pk_add_f32 v[234:235], v[234:235], v[242:243]
	v_pk_add_f32 v[236:237], v[236:237], v[244:245]
	v_pk_add_f32 v[238:239], v[238:239], v[246:247]
.Lpool_rows:
	s_waitcnt vmcnt(30)
	v_lshlrev_b32_e32 v240, 16, v96
	v_and_b32_e32 v241, 0xffff0000, v96
	v_lshlrev_b32_e32 v242, 16, v97
	v_and_b32_e32 v243, 0xffff0000, v97
	v_lshlrev_b32_e32 v244, 16, v98
	v_and_b32_e32 v245, 0xffff0000, v98
	v_lshlrev_b32_e32 v246, 16, v99
	v_and_b32_e32 v247, 0xffff0000, v99
	v_pk_add_f32 v[232:233], v[232:233], v[240:241]
	v_pk_add_f32 v[234:235], v[234:235], v[242:243]
	v_pk_add_f32 v[236:237], v[236:237], v[244:245]
	v_pk_add_f32 v[238:239], v[238:239], v[246:247]
	v_fma_f32 v248, s100, v232, -v240
	v_fma_f32 v249, s100, v233, -v241
	v_fma_f32 v250, s100, v234, -v242
	v_fma_f32 v251, s100, v235, -v243
	v_fma_f32 v8, s100, v236, -v244
	v_fma_f32 v9, s100, v237, -v245
	v_fma_f32 v10, s100, v238, -v246
	v_fma_f32 v11, s100, v239, -v247
	v_cvt_pk_bf16_f32 v12, v248, v249
	v_cvt_pk_bf16_f32 v13, v250, v251
	v_cvt_pk_bf16_f32 v14, v8, v9
	v_cvt_pk_bf16_f32 v15, v10, v11
	global_store_dwordx4 v16, v[12:15], s[98:99]
	s_add_u32 s98, s98, 0x1000
	s_addc_u32 s99, s99, 0
	v_lshlrev_b32_e32 v240, 16, v160
	v_and_b32_e32 v241, 0xffff0000, v160
	v_lshlrev_b32_e32 v242, 16, v161
	v_and_b32_e32 v243, 0xffff0000, v161
	v_lshlrev_b32_e32 v244, 16, v162
	v_and_b32_e32 v245, 0xffff0000, v162
	v_lshlrev_b32_e32 v246, 16, v163
	v_and_b32_e32 v247, 0xffff0000, v163
	v_pk_add_f32 v[232:233], v[232:233], v[240:241] neg_lo:[0,1] neg_hi:[0,1]
	v_pk_add_f32 v[234:235], v[234:235], v[242:243] neg_lo:[0,1] neg_hi:[0,1]
	v_pk_add_f32 v[236:237], v[236:237], v[244:245] neg_lo:[0,1] neg_hi:[0,1]
	v_pk_add_f32 v[238:239], v[238:239], v[246:247] neg_lo:[0,1] neg_hi:[0,1]
	s_waitcnt vmcnt(29)
	v_lshlrev_b32_e32 v240, 16, v100
	v_and_b32_e32 v241, 0xffff0000, v100
	v_lshlrev_b32_e32 v242, 16, v101
	v_and_b32_e32 v243, 0xffff0000, v101
	v_lshlrev_b32_e32 v244, 16, v102
	v_and_b32_e32 v245, 0xffff0000, v102
	v_lshlrev_b32_e32 v246, 16, v103
	v_and_b32_e32 v247, 0xffff0000, v103
	v_pk_add_f32 v[232:233], v[232:233], v[240:241]
	v_pk_add_f32 v[234:235], v[234:235], v[242:243]
	v_pk_add_f32 v[236:237], v[236:237], v[244:245]
	v_pk_add_f32 v[238:239], v[238:239], v[246:247]
	v_fma_f32 v248, s100, v232, -v240
	v_fma_f32 v249, s100, v233, -v241
	v_fma_f32 v250, s100, v234, -v242
	v_fma_f32 v251, s100, v235, -v243
	v_fma_f32 v8, s100, v236, -v244
	v_fma_f32 v9, s100, v237, -v245
	v_fma_f32 v10, s100, v238, -v246
	v_fma_f32 v11, s100, v239, -v247
	v_cvt_pk_bf16_f32 v12, v248, v249
	v_cvt_pk_bf16_f32 v13, v250, v251
	v_cvt_pk_bf16_f32 v14, v8, v9
	v_cvt_pk_bf16_f32 v15, v10, v11
	global_store_dwordx4 v16, v[12:15], s[98:99]
	s_add_u32 s98, s98, 0x1000
	s_addc_u32 s99, s99, 0
	v_lshlrev_b32_e32 v240, 16, v164
	v_and_b32_e32 v241, 0xffff0000, v164
	v_lshlrev_b32_e32 v242, 16, v165
	v_and_b32_e32 v243, 0xffff0000, v165
	v_lshlrev_b32_e32 v244, 16, v166
	v_and_b32_e32 v245, 0xffff0000, v166
	v_lshlrev_b32_e32 v246, 16, v167
	v_and_b32_e32 v247, 0xffff0000, v167
	v_pk_add_f32 v[232:233], v[232:233], v[240:241] neg_lo:[0,1] neg_hi:[0,1]
	v_pk_add_f32 v[234:235], v[234:235], v[242:243] neg_lo:[0,1] neg_hi:[0,1]
	v_pk_add_f32 v[236:237], v[236:237], v[244:245] neg_lo:[0,1] neg_hi:[0,1]
	v_pk_add_f32 v[238:239], v[238:239], v[246:247] neg_lo:[0,1] neg_hi:[0,1]
	s_waitcnt vmcnt(28)
	v_lshlrev_b32_e32 v240, 16, v104
	v_and_b32_e32 v241, 0xffff0000, v104
	v_lshlrev_b32_e32 v242, 16, v105
	v_and_b32_e32 v243, 0xffff0000, v105
	v_lshlrev_b32_e32 v244, 16, v106
	v_and_b32_e32 v245, 0xffff0000, v106
	v_lshlrev_b32_e32 v246, 16, v107
	v_and_b32_e32 v247, 0xffff0000, v107
	v_pk_add_f32 v[232:233], v[232:233], v[240:241]
	v_pk_add_f32 v[234:235], v[234:235], v[242:243]
	v_pk_add_f32 v[236:237], v[236:237], v[244:245]
	v_pk_add_f32 v[238:239], v[238:239], v[246:247]
	v_fma_f32 v248, s100, v232, -v240
	v_fma_f32 v249, s100, v233, -v241
	v_fma_f32 v250, s100, v234, -v242
	v_fma_f32 v251, s100, v235, -v243
	v_fma_f32 v8, s100, v236, -v244
	v_fma_f32 v9, s100, v237, -v245
	v_fma_f32 v10, s100, v238, -v246
	v_fma_f32 v11, s100, v239, -v247
	v_cvt_pk_bf16_f32 v12, v248, v249
	v_cvt_pk_bf16_f32 v13, v250, v251
	v_cvt_pk_bf16_f32 v14, v8, v9
	v_cvt_pk_bf16_f32 v15, v10, v11
	global_store_dwordx4 v16, v[12:15], s[98:99]
	s_add_u32 s98, s98, 0x1000
	s_addc_u32 s99, s99, 0
	v_lshlrev_b32_e32 v240, 16, v168
	v_and_b32_e32 v241, 0xffff0000, v168
	v_lshlrev_b32_e32 v242, 16, v169
	v_and_b32_e32 v243, 0xffff0000, v169
	v_lshlrev_b32_e32 v244, 16, v170
	v_and_b32_e32 v245, 0xffff0000, v170
	v_lshlrev_b32_e32 v246, 16, v171
	v_and_b32_e32 v247, 0xffff0000, v171
	v_pk_add_f32 v[232:233], v[232:233], v[240:241] neg_lo:[0,1] neg_hi:[0,1]
	v_pk_add_f32 v[234:235], v[234:235], v[242:243] neg_lo:[0,1] neg_hi:[0,1]
	v_pk_add_f32 v[236:237], v[236:237], v[244:245] neg_lo:[0,1] neg_hi:[0,1]
	v_pk_add_f32 v[238:239], v[238:239], v[246:247] neg_lo:[0,1] neg_hi:[0,1]
	s_waitcnt vmcnt(27)
	v_lshlrev_b32_e32 v240, 16, v108
	v_and_b32_e32 v241, 0xffff0000, v108
	v_lshlrev_b32_e32 v242, 16, v109
	v_and_b32_e32 v243, 0xffff0000, v109
	v_lshlrev_b32_e32 v244, 16, v110
	v_and_b32_e32 v245, 0xffff0000, v110
	v_lshlrev_b32_e32 v246, 16, v111
	v_and_b32_e32 v247, 0xffff0000, v111
	v_pk_add_f32 v[232:233], v[232:233], v[240:241]
	v_pk_add_f32 v[234:235], v[234:235], v[242:243]
	v_pk_add_f32 v[236:237], v[236:237], v[244:245]
	v_pk_add_f32 v[238:239], v[238:239], v[246:247]
	v_fma_f32 v248, s100, v232, -v240
	v_fma_f32 v249, s100, v233, -v241
	v_fma_f32 v250, s100, v234, -v242
	v_fma_f32 v251, s100, v235, -v243
	v_fma_f32 v8, s100, v236, -v244
	v_fma_f32 v9, s100, v237, -v245
	v_fma_f32 v10, s100, v238, -v246
	v_fma_f32 v11, s100, v239, -v247
	v_cvt_pk_bf16_f32 v12, v248, v249
	v_cvt_pk_bf16_f32 v13, v250, v251
	v_cvt_pk_bf16_f32 v14, v8, v9
	v_cvt_pk_bf16_f32 v15, v10, v11
	global_store_dwordx4 v16, v[12:15], s[98:99]
	s_add_u32 s98, s98, 0x1000
	s_addc_u32 s99, s99, 0
	v_lshlrev_b32_e32 v240, 16, v172
	v_and_b32_e32 v241, 0xffff0000, v172
	v_lshlrev_b32_e32 v242, 16, v173
	v_and_b32_e32 v243, 0xffff0000, v173
	v_lshlrev_b32_e32 v244, 16, v174
	v_and_b32_e32 v245, 0xffff0000, v174
	v_lshlrev_b32_e32 v246, 16, v175
	v_and_b32_e32 v247, 0xffff0000, v175
	v_pk_add_f32 v[232:233], v[232:233], v[240:241] neg_lo:[0,1] neg_hi:[0,1]
	v_pk_add_f32 v[234:235], v[234:235], v[242:243] neg_lo:[0,1] neg_hi:[0,1]
	v_pk_add_f32 v[236:237], v[236:237], v[244:245] neg_lo:[0,1] neg_hi:[0,1]
	v_pk_add_f32 v[238:239], v[238:239], v[246:247] neg_lo:[0,1] neg_hi:[0,1]
	s_waitcnt vmcnt(26)
	v_lshlrev_b32_e32 v240, 16, v112
	v_and_b32_e32 v241, 0xffff0000, v112
	v_lshlrev_b32_e32 v242, 16, v113
	v_and_b32_e32 v243, 0xffff0000, v113
	v_lshlrev_b32_e32 v244, 16, v114
	v_and_b32_e32 v245, 0xffff0000, v114
	v_lshlrev_b32_e32 v246, 16, v115
	v_and_b32_e32 v247, 0xffff0000, v115
	v_pk_add_f32 v[232:233], v[232:233], v[240:241]
	v_pk_add_f32 v[234:235], v[234:235], v[242:243]
	v_pk_add_f32 v[236:237], v[236:237], v[244:245]
	v_pk_add_f32 v[238:239], v[238:239], v[246:247]
	v_fma_f32 v248, s100, v232, -v240
	v_fma_f32 v249, s100, v233, -v241
	v_fma_f32 v250, s100, v234, -v242
	v_fma_f32 v251, s100, v235, -v243
	v_fma_f32 v8, s100, v236, -v244
	v_fma_f32 v9, s100, v237, -v245
	v_fma_f32 v10, s100, v238, -v246
	v_fma_f32 v11, s100, v239, -v247
	v_cvt_pk_bf16_f32 v12, v248, v249
	v_cvt_pk_bf16_f32 v13, v250, v251
	v_cvt_pk_bf16_f32 v14, v8, v9
	v_cvt_pk_bf16_f32 v15, v10, v11
	global_store_dwordx4 v16, v[12:15], s[98:99]
	s_add_u32 s98, s98, 0x1000
	s_addc_u32 s99, s99, 0
	v_lshlrev_b32_e32 v240, 16, v176
	v_and_b32_e32 v241, 0xffff0000, v176
	v_lshlrev_b32_e32 v242, 16, v177
	v_and_b32_e32 v243, 0xffff0000, v177
	v_lshlrev_b32_e32 v244, 16, v178
	v_and_b32_e32 v245, 0xffff0000, v178
	v_lshlrev_b32_e32 v246, 16, v179
	v_and_b32_e32 v247, 0xffff0000, v179
	v_pk_add_f32 v[232:233], v[232:233], v[240:241] neg_lo:[0,1] neg_hi:[0,1]
	v_pk_add_f32 v[234:235], v[234:235], v[242:243] neg_lo:[0,1] neg_hi:[0,1]
	v_pk_add_f32 v[236:237], v[236:237], v[244:245] neg_lo:[0,1] neg_hi:[0,1]
	v_pk_add_f32 v[238:239], v[238:239], v[246:247] neg_lo:[0,1] neg_hi:[0,1]
	s_waitcnt vmcnt(25)
	v_lshlrev_b32_e32 v240, 16, v116
	v_and_b32_e32 v241, 0xffff0000, v116
	v_lshlrev_b32_e32 v242, 16, v117
	v_and_b32_e32 v243, 0xffff0000, v117
	v_lshlrev_b32_e32 v244, 16, v118
	v_and_b32_e32 v245, 0xffff0000, v118
	v_lshlrev_b32_e32 v246, 16, v119
	v_and_b32_e32 v247, 0xffff0000, v119
	v_pk_add_f32 v[232:233], v[232:233], v[240:241]
	v_pk_add_f32 v[234:235], v[234:235], v[242:243]
	v_pk_add_f32 v[236:237], v[236:237], v[244:245]
	v_pk_add_f32 v[238:239], v[238:239], v[246:247]
	v_fma_f32 v248, s100, v232, -v240
	v_fma_f32 v249, s100, v233, -v241
	v_fma_f32 v250, s100, v234, -v242
	v_fma_f32 v251, s100, v235, -v243
	v_fma_f32 v8, s100, v236, -v244
	v_fma_f32 v9, s100, v237, -v245
	v_fma_f32 v10, s100, v238, -v246
	v_fma_f32 v11, s100, v239, -v247
	v_cvt_pk_bf16_f32 v12, v248, v249
	v_cvt_pk_bf16_f32 v13, v250, v251
	v_cvt_pk_bf16_f32 v14, v8, v9
	v_cvt_pk_bf16_f32 v15, v10, v11
	global_store_dwordx4 v16, v[12:15], s[98:99]
	s_add_u32 s98, s98, 0x1000
	s_addc_u32 s99, s99, 0
	v_lshlrev_b32_e32 v240, 16, v180
	v_and_b32_e32 v241, 0xffff0000, v180
	v_lshlrev_b32_e32 v242, 16, v181
	v_and_b32_e32 v243, 0xffff0000, v181
	v_lshlrev_b32_e32 v244, 16, v182
	v_and_b32_e32 v245, 0xffff0000, v182
	v_lshlrev_b32_e32 v246, 16, v183
	v_and_b32_e32 v247, 0xffff0000, v183
	v_pk_add_f32 v[232:233], v[232:233], v[240:241] neg_lo:[0,1] neg_hi:[0,1]
	v_pk_add_f32 v[234:235], v[234:235], v[242:243] neg_lo:[0,1] neg_hi:[0,1]
	v_pk_add_f32 v[236:237], v[236:237], v[244:245] neg_lo:[0,1] neg_hi:[0,1]
	v_pk_add_f32 v[238:239], v[238:239], v[246:247] neg_lo:[0,1] neg_hi:[0,1]
	s_waitcnt vmcnt(24)
	v_lshlrev_b32_e32 v240, 16, v120
	v_and_b32_e32 v241, 0xffff0000, v120
	v_lshlrev_b32_e32 v242, 16, v121
	v_and_b32_e32 v243, 0xffff0000, v121
	v_lshlrev_b32_e32 v244, 16, v122
	v_and_b32_e32 v245, 0xffff0000, v122
	v_lshlrev_b32_e32 v246, 16, v123
	v_and_b32_e32 v247, 0xffff0000, v123
	v_pk_add_f32 v[232:233], v[232:233], v[240:241]
	v_pk_add_f32 v[234:235], v[234:235], v[242:243]
	v_pk_add_f32 v[236:237], v[236:237], v[244:245]
	v_pk_add_f32 v[238:239], v[238:239], v[246:247]
	v_fma_f32 v248, s100, v232, -v240
	v_fma_f32 v249, s100, v233, -v241
	v_fma_f32 v250, s100, v234, -v242
	v_fma_f32 v251, s100, v235, -v243
	v_fma_f32 v8, s100, v236, -v244
	v_fma_f32 v9, s100, v237, -v245
	v_fma_f32 v10, s100, v238, -v246
	v_fma_f32 v11, s100, v239, -v247
	v_cvt_pk_bf16_f32 v12, v248, v249
	v_cvt_pk_bf16_f32 v13, v250, v251
	v_cvt_pk_bf16_f32 v14, v8, v9
	v_cvt_pk_bf16_f32 v15, v10, v11
	global_store_dwordx4 v16, v[12:15], s[98:99]
	s_add_u32 s98, s98, 0x1000
	s_addc_u32 s99, s99, 0
	v_lshlrev_b32_e32 v240, 16, v184
	v_and_b32_e32 v241, 0xffff0000, v184
	v_lshlrev_b32_e32 v242, 16, v185
	v_and_b32_e32 v243, 0xffff0000, v185
	v_lshlrev_b32_e32 v244, 16, v186
	v_and_b32_e32 v245, 0xffff0000, v186
	v_lshlrev_b32_e32 v246, 16, v187
	v_and_b32_e32 v247, 0xffff0000, v187
	v_pk_add_f32 v[232:233], v[232:233], v[240:241] neg_lo:[0,1] neg_hi:[0,1]
	v_pk_add_f32 v[234:235], v[234:235], v[242:243] neg_lo:[0,1] neg_hi:[0,1]
	v_pk_add_f32 v[236:237], v[236:237], v[244:245] neg_lo:[0,1] neg_hi:[0,1]
	v_pk_add_f32 v[238:239], v[238:239], v[246:247] neg_lo:[0,1] neg_hi:[0,1]
	s_waitcnt vmcnt(23)
	v_lshlrev_b32_e32 v240, 16, v124
	v_and_b32_e32 v241, 0xffff0000, v124
	v_lshlrev_b32_e32 v242, 16, v125
	v_and_b32_e32 v243, 0xffff0000, v125
	v_lshlrev_b32_e32 v244, 16, v126
	v_and_b32_e32 v245, 0xffff0000, v126
	v_lshlrev_b32_e32 v246, 16, v127
	v_and_b32_e32 v247, 0xffff0000, v127
	v_pk_add_f32 v[232:233], v[232:233], v[240:241]
	v_pk_add_f32 v[234:235], v[234:235], v[242:243]
	v_pk_add_f32 v[236:237], v[236:237], v[244:245]
	v_pk_add_f32 v[238:239], v[238:239], v[246:247]
	v_fma_f32 v248, s100, v232, -v240
	v_fma_f32 v249, s100, v233, -v241
	v_fma_f32 v250, s100, v234, -v242
	v_fma_f32 v251, s100, v235, -v243
	v_fma_f32 v8, s100, v236, -v244
	v_fma_f32 v9, s100, v237, -v245
	v_fma_f32 v10, s100, v238, -v246
	v_fma_f32 v11, s100, v239, -v247
	v_cvt_pk_bf16_f32 v12, v248, v249
	v_cvt_pk_bf16_f32 v13, v250, v251
	v_cvt_pk_bf16_f32 v14, v8, v9
	v_cvt_pk_bf16_f32 v15, v10, v11
	global_store_dwordx4 v16, v[12:15], s[98:99]
	s_add_u32 s98, s98, 0x1000
	s_addc_u32 s99, s99, 0
	v_lshlrev_b32_e32 v240, 16, v188
	v_and_b32_e32 v241, 0xffff0000, v188
	v_lshlrev_b32_e32 v242, 16, v189
	v_and_b32_e32 v243, 0xffff0000, v189
	v_lshlrev_b32_e32 v244, 16, v190
	v_and_b32_e32 v245, 0xffff0000, v190
	v_lshlrev_b32_e32 v246, 16, v191
	v_and_b32_e32 v247, 0xffff0000, v191
	v_pk_add_f32 v[232:233], v[232:233], v[240:241] neg_lo:[0,1] neg_hi:[0,1]
	v_pk_add_f32 v[234:235], v[234:235], v[242:243] neg_lo:[0,1] neg_hi:[0,1]
	v_pk_add_f32 v[236:237], v[236:237], v[244:245] neg_lo:[0,1] neg_hi:[0,1]
	v_pk_add_f32 v[238:239], v[238:239], v[246:247] neg_lo:[0,1] neg_hi:[0,1]
	s_waitcnt vmcnt(22)
	v_lshlrev_b32_e32 v240, 16, v128
	v_and_b32_e32 v241, 0xffff0000, v128
	v_lshlrev_b32_e32 v242, 16, v129
	v_and_b32_e32 v243, 0xffff0000, v129
	v_lshlrev_b32_e32 v244, 16, v130
	v_and_b32_e32 v245, 0xffff0000, v130
	v_lshlrev_b32_e32 v246, 16, v131
	v_and_b32_e32 v247, 0xffff0000, v131
	v_pk_add_f32 v[232:233], v[232:233], v[240:241]
	v_pk_add_f32 v[234:235], v[234:235], v[242:243]
	v_pk_add_f32 v[236:237], v[236:237], v[244:245]
	v_pk_add_f32 v[238:239], v[238:239], v[246:247]
	v_fma_f32 v248, s100, v232, -v240
	v_fma_f32 v249, s100, v233, -v241
	v_fma_f32 v250, s100, v234, -v242
	v_fma_f32 v251, s100, v235, -v243
	v_fma_f32 v8, s100, v236, -v244
	v_fma_f32 v9, s100, v237, -v245
	v_fma_f32 v10, s100, v238, -v246
	v_fma_f32 v11, s100, v239, -v247
	v_cvt_pk_bf16_f32 v12, v248, v249
	v_cvt_pk_bf16_f32 v13, v250, v251
	v_cvt_pk_bf16_f32 v14, v8, v9
	v_cvt_pk_bf16_f32 v15, v10, v11
	global_store_dwordx4 v16, v[12:15], s[98:99]
	s_add_u32 s98, s98, 0x1000
	s_addc_u32 s99, s99, 0
	v_lshlrev_b32_e32 v240, 16, v192
	v_and_b32_e32 v241, 0xffff0000, v192
	v_lshlrev_b32_e32 v242, 16, v193
	v_and_b32_e32 v243, 0xffff0000, v193
	v_lshlrev_b32_e32 v244, 16, v194
	v_and_b32_e32 v245, 0xffff0000, v194
	v_lshlrev_b32_e32 v246, 16, v195
	v_and_b32_e32 v247, 0xffff0000, v195
	v_pk_add_f32 v[232:233], v[232:233], v[240:241] neg_lo:[0,1] neg_hi:[0,1]
	v_pk_add_f32 v[234:235], v[234:235], v[242:243] neg_lo:[0,1] neg_hi:[0,1]
	v_pk_add_f32 v[236:237], v[236:237], v[244:245] neg_lo:[0,1] neg_hi:[0,1]
	v_pk_add_f32 v[238:239], v[238:239], v[246:247] neg_lo:[0,1] neg_hi:[0,1]
	s_waitcnt vmcnt(21)
	v_lshlrev_b32_e32 v240, 16, v132
	v_and_b32_e32 v241, 0xffff0000, v132
	v_lshlrev_b32_e32 v242, 16, v133
	v_and_b32_e32 v243, 0xffff0000, v133
	v_lshlrev_b32_e32 v244, 16, v134
	v_and_b32_e32 v245, 0xffff0000, v134
	v_lshlrev_b32_e32 v246, 16, v135
	v_and_b32_e32 v247, 0xffff0000, v135
	v_pk_add_f32 v[232:233], v[232:233], v[240:241]
	v_pk_add_f32 v[234:235], v[234:235], v[242:243]
	v_pk_add_f32 v[236:237], v[236:237], v[244:245]
	v_pk_add_f32 v[238:239], v[238:239], v[246:247]
	v_fma_f32 v248, s100, v232, -v240
	v_fma_f32 v249, s100, v233, -v241
	v_fma_f32 v250, s100, v234, -v242
	v_fma_f32 v251, s100, v235, -v243
	v_fma_f32 v8, s100, v236, -v244
	v_fma_f32 v9, s100, v237, -v245
	v_fma_f32 v10, s100, v238, -v246
	v_fma_f32 v11, s100, v239, -v247
	v_cvt_pk_bf16_f32 v12, v248, v249
	v_cvt_pk_bf16_f32 v13, v250, v251
	v_cvt_pk_bf16_f32 v14, v8, v9
	v_cvt_pk_bf16_f32 v15, v10, v11
	global_store_dwordx4 v16, v[12:15], s[98:99]
	s_add_u32 s98, s98, 0x1000
	s_addc_u32 s99, s99, 0
	v_lshlrev_b32_e32 v240, 16, v196
	v_and_b32_e32 v241, 0xffff0000, v196
	v_lshlrev_b32_e32 v242, 16, v197
	v_and_b32_e32 v243, 0xffff0000, v197
	v_lshlrev_b32_e32 v244, 16, v198
	v_and_b32_e32 v245, 0xffff0000, v198
	v_lshlrev_b32_e32 v246, 16, v199
	v_and_b32_e32 v247, 0xffff0000, v199
	v_pk_add_f32 v[232:233], v[232:233], v[240:241] neg_lo:[0,1] neg_hi:[0,1]
	v_pk_add_f32 v[234:235], v[234:235], v[242:243] neg_lo:[0,1] neg_hi:[0,1]
	v_pk_add_f32 v[236:237], v[236:237], v[244:245] neg_lo:[0,1] neg_hi:[0,1]
	v_pk_add_f32 v[238:239], v[238:239], v[246:247] neg_lo:[0,1] neg_hi:[0,1]
	s_waitcnt vmcnt(20)
	v_lshlrev_b32_e32 v240, 16, v136
	v_and_b32_e32 v241, 0xffff0000, v136
	v_lshlrev_b32_e32 v242, 16, v137
	v_and_b32_e32 v243, 0xffff0000, v137
	v_lshlrev_b32_e32 v244, 16, v138
	v_and_b32_e32 v245, 0xffff0000, v138
	v_lshlrev_b32_e32 v246, 16, v139
	v_and_b32_e32 v247, 0xffff0000, v139
	v_pk_add_f32 v[232:233], v[232:233], v[240:241]
	v_pk_add_f32 v[234:235], v[234:235], v[242:243]
	v_pk_add_f32 v[236:237], v[236:237], v[244:245]
	v_pk_add_f32 v[238:239], v[238:239], v[246:247]
	v_fma_f32 v248, s100, v232, -v240
	v_fma_f32 v249, s100, v233, -v241
	v_fma_f32 v250, s100, v234, -v242
	v_fma_f32 v251, s100, v235, -v243
	v_fma_f32 v8, s100, v236, -v244
	v_fma_f32 v9, s100, v237, -v245
	v_fma_f32 v10, s100, v238, -v246
	v_fma_f32 v11, s100, v239, -v247
	v_cvt_pk_bf16_f32 v12, v248, v249
	v_cvt_pk_bf16_f32 v13, v250, v251
	v_cvt_pk_bf16_f32 v14, v8, v9
	v_cvt_pk_bf16_f32 v15, v10, v11
	global_store_dwordx4 v16, v[12:15], s[98:99]
	s_add_u32 s98, s98, 0x1000
	s_addc_u32 s99, s99, 0
	v_lshlrev_b32_e32 v240, 16, v200
	v_and_b32_e32 v241, 0xffff0000, v200
	v_lshlrev_b32_e32 v242, 16, v201
	v_and_b32_e32 v243, 0xffff0000, v201
	v_lshlrev_b32_e32 v244, 16, v202
	v_and_b32_e32 v245, 0xffff0000, v202
	v_lshlrev_b32_e32 v246, 16, v203
	v_and_b32_e32 v247, 0xffff0000, v203
	v_pk_add_f32 v[232:233], v[232:233], v[240:241] neg_lo:[0,1] neg_hi:[0,1]
	v_pk_add_f32 v[234:235], v[234:235], v[242:243] neg_lo:[0,1] neg_hi:[0,1]
	v_pk_add_f32 v[236:237], v[236:237], v[244:245] neg_lo:[0,1] neg_hi:[0,1]
	v_pk_add_f32 v[238:239], v[238:239], v[246:247] neg_lo:[0,1] neg_hi:[0,1]
	s_waitcnt vmcnt(19)
	v_lshlrev_b32_e32 v240, 16, v140
	v_and_b32_e32 v241, 0xffff0000, v140
	v_lshlrev_b32_e32 v242, 16, v141
	v_and_b32_e32 v243, 0xffff0000, v141
	v_lshlrev_b32_e32 v244, 16, v142
	v_and_b32_e32 v245, 0xffff0000, v142
	v_lshlrev_b32_e32 v246, 16, v143
	v_and_b32_e32 v247, 0xffff0000, v143
	v_pk_add_f32 v[232:233], v[232:233], v[240:241]
	v_pk_add_f32 v[234:235], v[234:235], v[242:243]
	v_pk_add_f32 v[236:237], v[236:237], v[244:245]
	v_pk_add_f32 v[238:239], v[238:239], v[246:247]
	v_fma_f32 v248, s100, v232, -v240
	v_fma_f32 v249, s100, v233, -v241
	v_fma_f32 v250, s100, v234, -v242
	v_fma_f32 v251, s100, v235, -v243
	v_fma_f32 v8, s100, v236, -v244
	v_fma_f32 v9, s100, v237, -v245
	v_fma_f32 v10, s100, v238, -v246
	v_fma_f32 v11, s100, v239, -v247
	v_cvt_pk_bf16_f32 v12, v248, v249
	v_cvt_pk_bf16_f32 v13, v250, v251
	v_cvt_pk_bf16_f32 v14, v8, v9
	v_cvt_pk_bf16_f32 v15, v10, v11
	global_store_dwordx4 v16, v[12:15], s[98:99]
	s_add_u32 s98, s98, 0x1000
	s_addc_u32 s99, s99, 0
	v_lshlrev_b32_e32 v240, 16, v208
	v_and_b32_e32 v241, 0xffff0000, v208
	v_lshlrev_b32_e32 v242, 16, v209
	v_and_b32_e32 v243, 0xffff0000, v209
	v_lshlrev_b32_e32 v244, 16, v210
	v_and_b32_e32 v245, 0xffff0000, v210
	v_lshlrev_b32_e32 v246, 16, v211
	v_and_b32_e32 v247, 0xffff0000, v211
	v_pk_add_f32 v[232:233], v[232:233], v[240:241] neg_lo:[0,1] neg_hi:[0,1]
	v_pk_add_f32 v[234:235], v[234:235], v[242:243] neg_lo:[0,1] neg_hi:[0,1]
	v_pk_add_f32 v[236:237], v[236:237], v[244:245] neg_lo:[0,1] neg_hi:[0,1]
	v_pk_add_f32 v[238:239], v[238:239], v[246:247] neg_lo:[0,1] neg_hi:[0,1]
	s_waitcnt vmcnt(18)
	v_lshlrev_b32_e32 v240, 16, v144
	v_and_b32_e32 v241, 0xffff0000, v144
	v_lshlrev_b32_e32 v242, 16, v145
	v_and_b32_e32 v243, 0xffff0000, v145
	v_lshlrev_b32_e32 v244, 16, v146
	v_and_b32_e32 v245, 0xffff0000, v146
	v_lshlrev_b32_e32 v246, 16, v147
	v_and_b32_e32 v247, 0xffff0000, v147
	v_pk_add_f32 v[232:233], v[232:233], v[240:241]
	v_pk_add_f32 v[234:235], v[234:235], v[242:243]
	v_pk_add_f32 v[236:237], v[236:237], v[244:245]
	v_pk_add_f32 v[238:239], v[238:239], v[246:247]
	v_fma_f32 v248, s100, v232, -v240
	v_fma_f32 v249, s100, v233, -v241
	v_fma_f32 v250, s100, v234, -v242
	v_fma_f32 v251, s100, v235, -v243
	v_fma_f32 v8, s100, v236, -v244
	v_fma_f32 v9, s100, v237, -v245
	v_fma_f32 v10, s100, v238, -v246
	v_fma_f32 v11, s100, v239, -v247
	v_cvt_pk_bf16_f32 v12, v248, v249
	v_cvt_pk_bf16_f32 v13, v250, v251
	v_cvt_pk_bf16_f32 v14, v8, v9
	v_cvt_pk_bf16_f32 v15, v10, v11
	global_store_dwordx4 v16, v[12:15], s[98:99]
	s_add_u32 s98, s98, 0x1000
	s_addc_u32 s99, s99, 0
	v_lshlrev_b32_e32 v240, 16, v212
	v_and_b32_e32 v241, 0xffff0000, v212
	v_lshlrev_b32_e32 v242, 16, v213
	v_and_b32_e32 v243, 0xffff0000, v213
	v_lshlrev_b32_e32 v244, 16, v214
	v_and_b32_e32 v245, 0xffff0000, v214
	v_lshlrev_b32_e32 v246, 16, v215
	v_and_b32_e32 v247, 0xffff0000, v215
	v_pk_add_f32 v[232:233], v[232:233], v[240:241] neg_lo:[0,1] neg_hi:[0,1]
	v_pk_add_f32 v[234:235], v[234:235], v[242:243] neg_lo:[0,1] neg_hi:[0,1]
	v_pk_add_f32 v[236:237], v[236:237], v[244:245] neg_lo:[0,1] neg_hi:[0,1]
	v_pk_add_f32 v[238:239], v[238:239], v[246:247] neg_lo:[0,1] neg_hi:[0,1]
	s_waitcnt vmcnt(17)
	v_lshlrev_b32_e32 v240, 16, v148
	v_and_b32_e32 v241, 0xffff0000, v148
	v_lshlrev_b32_e32 v242, 16, v149
	v_and_b32_e32 v243, 0xffff0000, v149
	v_lshlrev_b32_e32 v244, 16, v150
	v_and_b32_e32 v245, 0xffff0000, v150
	v_lshlrev_b32_e32 v246, 16, v151
	v_and_b32_e32 v247, 0xffff0000, v151
	v_pk_add_f32 v[232:233], v[232:233], v[240:241]
	v_pk_add_f32 v[234:235], v[234:235], v[242:243]
	v_pk_add_f32 v[236:237], v[236:237], v[244:245]
	v_pk_add_f32 v[238:239], v[238:239], v[246:247]
	v_fma_f32 v248, s100, v232, -v240
	v_fma_f32 v249, s100, v233, -v241
	v_fma_f32 v250, s100, v234, -v242
	v_fma_f32 v251, s100, v235, -v243
	v_fma_f32 v8, s100, v236, -v244
	v_fma_f32 v9, s100, v237, -v245
	v_fma_f32 v10, s100, v238, -v246
	v_fma_f32 v11, s100, v239, -v247
	v_cvt_pk_bf16_f32 v12, v248, v249
	v_cvt_pk_bf16_f32 v13, v250, v251
	v_cvt_pk_bf16_f32 v14, v8, v9
	v_cvt_pk_bf16_f32 v15, v10, v11
	global_store_dwordx4 v16, v[12:15], s[98:99]
	s_add_u32 s98, s98, 0x1000
	s_addc_u32 s99, s99, 0
	v_lshlrev_b32_e32 v240, 16, v216
	v_and_b32_e32 v241, 0xffff0000, v216
	v_lshlrev_b32_e32 v242, 16, v217
	v_and_b32_e32 v243, 0xffff0000, v217
	v_lshlrev_b32_e32 v244, 16, v218
	v_and_b32_e32 v245, 0xffff0000, v218
	v_lshlrev_b32_e32 v246, 16, v219
	v_and_b32_e32 v247, 0xffff0000, v219
	v_pk_add_f32 v[232:233], v[232:233], v[240:241] neg_lo:[0,1] neg_hi:[0,1]
	v_pk_add_f32 v[234:235], v[234:235], v[242:243] neg_lo:[0,1] neg_hi:[0,1]
	v_pk_add_f32 v[236:237], v[236:237], v[244:245] neg_lo:[0,1] neg_hi:[0,1]
	v_pk_add_f32 v[238:239], v[238:239], v[246:247] neg_lo:[0,1] neg_hi:[0,1]
	s_waitcnt vmcnt(16)
	v_lshlrev_b32_e32 v240, 16, v152
	v_and_b32_e32 v241, 0xffff0000, v152
	v_lshlrev_b32_e32 v242, 16, v153
	v_and_b32_e32 v243, 0xffff0000, v153
	v_lshlrev_b32_e32 v244, 16, v154
	v_and_b32_e32 v245, 0xffff0000, v154
	v_lshlrev_b32_e32 v246, 16, v155
	v_and_b32_e32 v247, 0xffff0000, v155
	v_pk_add_f32 v[232:233], v[232:233], v[240:241]
	v_pk_add_f32 v[234:235], v[234:235], v[242:243]
	v_pk_add_f32 v[236:237], v[236:237], v[244:245]
	v_pk_add_f32 v[238:239], v[238:239], v[246:247]
	v_fma_f32 v248, s100, v232, -v240
	v_fma_f32 v249, s100, v233, -v241
	v_fma_f32 v250, s100, v234, -v242
	v_fma_f32 v251, s100, v235, -v243
	v_fma_f32 v8, s100, v236, -v244
	v_fma_f32 v9, s100, v237, -v245
	v_fma_f32 v10, s100, v238, -v246
	v_fma_f32 v11, s100, v239, -v247
	v_cvt_pk_bf16_f32 v12, v248, v249
	v_cvt_pk_bf16_f32 v13, v250, v251
	v_cvt_pk_bf16_f32 v14, v8, v9
	v_cvt_pk_bf16_f32 v15, v10, v11
	global_store_dwordx4 v16, v[12:15], s[98:99]
	s_add_u32 s98, s98, 0x1000
	s_addc_u32 s99, s99, 0
	v_lshlrev_b32_e32 v240, 16, v220
	v_and_b32_e32 v241, 0xffff0000, v220
	v_lshlrev_b32_e32 v242, 16, v221
	v_and_b32_e32 v243, 0xffff0000, v221
	v_lshlrev_b32_e32 v244, 16, v222
	v_and_b32_e32 v245, 0xffff0000, v222
	v_lshlrev_b32_e32 v246, 16, v223
	v_and_b32_e32 v247, 0xffff0000, v223
	v_pk_add_f32 v[232:233], v[232:233], v[240:241] neg_lo:[0,1] neg_hi:[0,1]
	v_pk_add_f32 v[234:235], v[234:235], v[242:243] neg_lo:[0,1] neg_hi:[0,1]
	v_pk_add_f32 v[236:237], v[236:237], v[244:245] neg_lo:[0,1] neg_hi:[0,1]
	v_pk_add_f32 v[238:239], v[238:239], v[246:247] neg_lo:[0,1] neg_hi:[0,1]
	s_waitcnt vmcnt(15)
	v_lshlrev_b32_e32 v240, 16, v156
	v_and_b32_e32 v241, 0xffff0000, v156
	v_lshlrev_b32_e32 v242, 16, v157
	v_and_b32_e32 v243, 0xffff0000, v157
	v_lshlrev_b32_e32 v244, 16, v158
	v_and_b32_e32 v245, 0xffff0000, v158
	v_lshlrev_b32_e32 v246, 16, v159
	v_and_b32_e32 v247, 0xffff0000, v159
	v_pk_add_f32 v[232:233], v[232:233], v[240:241]
	v_pk_add_f32 v[234:235], v[234:235], v[242:243]
	v_pk_add_f32 v[236:237], v[236:237], v[244:245]
	v_pk_add_f32 v[238:239], v[238:239], v[246:247]
	v_fma_f32 v248, s100, v232, -v240
	v_fma_f32 v249, s100, v233, -v241
	v_fma_f32 v250, s100, v234, -v242
	v_fma_f32 v251, s100, v235, -v243
	v_fma_f32 v8, s100, v236, -v244
	v_fma_f32 v9, s100, v237, -v245
	v_fma_f32 v10, s100, v238, -v246
	v_fma_f32 v11, s100, v239, -v247
	v_cvt_pk_bf16_f32 v12, v248, v249
	v_cvt_pk_bf16_f32 v13, v250, v251
	v_cvt_pk_bf16_f32 v14, v8, v9
	v_cvt_pk_bf16_f32 v15, v10, v11
	global_store_dwordx4 v16, v[12:15], s[98:99]
	s_add_u32 s98, s98, 0x1000
	s_addc_u32 s99, s99, 0
	v_lshlrev_b32_e32 v240, 16, v228
	v_and_b32_e32 v241, 0xffff0000, v228
	v_lshlrev_b32_e32 v242, 16, v229
	v_and_b32_e32 v243, 0xffff0000, v229
	v_lshlrev_b32_e32 v244, 16, v230
	v_and_b32_e32 v245, 0xffff0000, v230
	v_lshlrev_b32_e32 v246, 16, v231
	v_and_b32_e32 v247, 0xffff0000, v231
	v_pk_add_f32 v[232:233], v[232:233], v[240:241] neg_lo:[0,1] neg_hi:[0,1]
	v_pk_add_f32 v[234:235], v[234:235], v[242:243] neg_lo:[0,1] neg_hi:[0,1]
	v_pk_add_f32 v[236:237], v[236:237], v[244:245] neg_lo:[0,1] neg_hi:[0,1]
	v_pk_add_f32 v[238:239], v[238:239], v[246:247] neg_lo:[0,1] neg_hi:[0,1]
	s_add_u32 s17, s17, 1
	s_cmp_lt_u32 s17, 2
	s_cbranch_scc1 .Lpool_chunk
	s_branch .LBB0_197

	.amdhsa_kernel _Z6mk_fwd4Args
		.amdhsa_group_segment_fixed_size 0
		.amdhsa_private_segment_fixed_size 0
		.amdhsa_kernarg_size 424
		.amdhsa_user_sgpr_count 2
		.amdhsa_user_sgpr_dispatch_ptr 0
		.amdhsa_user_sgpr_queue_ptr 0
		.amdhsa_user_sgpr_kernarg_segment_ptr 1
		.amdhsa_user_sgpr_dispatch_id 0
		.amdhsa_user_sgpr_kernarg_preload_length 0
		.amdhsa_user_sgpr_kernarg_preload_offset 0
		.amdhsa_user_sgpr_private_segment_size 0
		.amdhsa_uses_dynamic_stack 0
		.amdhsa_enable_private_segment 0
		.amdhsa_system_sgpr_workgroup_id_x 1
		.amdhsa_system_sgpr_workgroup_id_y 0
		.amdhsa_system_sgpr_workgroup_id_z 0
		.amdhsa_system_sgpr_workgroup_info 0
		.amdhsa_system_vgpr_workitem_id 2
		.amdhsa_next_free_vgpr 255
		.amdhsa_next_free_sgpr 102
		.amdhsa_accum_offset 256
		.amdhsa_reserve_vcc 1
		.amdhsa_float_round_mode_32 0
		.amdhsa_float_round_mode_16_64 0
		.amdhsa_float_denorm_mode_32 3
		.amdhsa_float_denorm_mode_16_64 3
		.amdhsa_dx10_clamp 1
		.amdhsa_ieee_mode 1
		.amdhsa_fp16_overflow 0
		.amdhsa_tg_split 0
		.amdhsa_exception_fp_ieee_invalid_op 0
		.amdhsa_exception_fp_denorm_src 0
		.amdhsa_exception_fp_ieee_div_zero 0
		.amdhsa_exception_fp_ieee_overflow 0
		.amdhsa_exception_fp_ieee_underflow 0
		.amdhsa_exception_fp_ieee_inexact 0
		.amdhsa_exception_int_div_zero 0
	.end_amdhsa_kernel

amdhsa.kernels:
  - .agpr_count:     0
    .args:
      - .offset:         0
        .size:           168
        .value_kind:     by_value
      - .offset:         168
        .size:           4
        .value_kind:     hidden_block_count_x
      - .offset:         172
        .size:           4
        .value_kind:     hidden_block_count_y
      - .offset:         176
        .size:           4
        .value_kind:     hidden_block_count_z
      - .offset:         180
        .size:           2
        .value_kind:     hidden_group_size_x
      - .offset:         182
        .size:           2
        .value_kind:     hidden_group_size_y
      - .offset:         184
        .size:           2
        .value_kind:     hidden_group_size_z
      - .offset:         186
        .size:           2
        .value_kind:     hidden_remainder_x
      - .offset:         188
        .size:           2
        .value_kind:     hidden_remainder_y
      - .offset:         190
        .size:           2
        .value_kind:     hidden_remainder_z
      - .offset:         208
        .size:           8
        .value_kind:     hidden_global_offset_x
      - .offset:         216
        .size:           8
        .value_kind:     hidden_global_offset_y
      - .offset:         224
        .size:           8
        .value_kind:     hidden_global_offset_z
      - .offset:         232
        .size:           2
        .value_kind:     hidden_grid_dims
      - .offset:         256
        .size:           8
        .value_kind:     hidden_multigrid_sync_arg
      - .offset:         288
        .size:           4
        .value_kind:     hidden_dynamic_lds_size
    .group_segment_fixed_size: 0
    .kernarg_segment_align: 8
    .kernarg_segment_size: 424
    .language:       OpenCL C
    .language_version:
      - 2
      - 0
    .max_flat_workgroup_size: 512
    .name:           _Z6mk_fwd4Args
    .private_segment_fixed_size: 0
    .sgpr_count:     108
    .sgpr_spill_count: 4
    .symbol:         _Z6mk_fwd4Args.kd
    .uniform_work_group_size: 1
    .uses_dynamic_stack: false
    .vgpr_count:     255
    .vgpr_spill_count: 0
    .wavefront_size: 64
